# diff item epilogue: the seven remaining subln (g) loads hoisted next to the first one, single vmcnt wait before the first store
# baseline (speedup 1.0000x reference)
; DI void phase_diff(KP p, int layer, u16* sm) {
;     ...
;     __builtin_amdgcn_s_setprio(0);
;     const int lsrc = (r & 15) + ((r >> 4) << 5);
;     const float l0 = __shfl(L4[0][0], lsrc), l1 = __shfl(L4[1][0], lsrc);
;     const float i0 = 1.f / l0, i1 = lam / l1;
;     float ss = 0.f;
; #pragma unroll
;     for (int mb = 0; mb < 2; ++mb)
; #pragma unroll
;       for (int i = 0; i < 16; ++i) { const float v = O[0][mb][i] * i0 - O[1][mb][i] * i1; O[0][mb][i] = v; ss += v * v; }
;     ss += __shfl_xor(ss, 32);
;     const float inv = rsqrtf(ss * (1.f / 64.f) + 1e-6f) * (1.f - lam_init);
;     u16* op = p.o + (size_t)(b * S + tq) * 1024 + head * 64;
.LBB0_462:
	s_setprio 0
	s_nop 7
	ds_bpermute_b32 v10, v238, v196
	ds_bpermute_b32 v11, v238, v200
	s_mov_b32 s31, s13
	s_add_i32 s36, s36, s74
	s_cmpk_lt_i32 s36, 0x200
	s_waitcnt lgkmcnt(1)
	v_div_scale_f32 v12, s[6:7], v10, v10, 1.0
	v_rcp_f32_e32 v13, v12
	s_nop 0
	v_fma_f32 v80, -v12, v13, 1.0
	v_fmac_f32_e32 v13, v80, v13
	v_div_scale_f32 v80, vcc, 1.0, v10, 1.0
	v_mul_f32_e32 v81, v80, v13
	v_fma_f32 v82, -v12, v81, v80
	v_fmac_f32_e32 v81, v82, v13
	v_fma_f32 v12, -v12, v81, v80
	v_div_fmas_f32 v12, v12, v13, v81
	v_div_fixup_f32 v80, v12, v10, 1.0
	s_waitcnt lgkmcnt(0)
	v_div_scale_f32 v10, s[6:7], v11, v11, v248
	v_rcp_f32_e32 v12, v10
	s_nop 0
	v_fma_f32 v13, -v10, v12, 1.0
	v_fmac_f32_e32 v12, v13, v12
	v_div_scale_f32 v13, vcc, v248, v11, v248
	v_mul_f32_e32 v81, v13, v12
	v_fma_f32 v82, -v10, v81, v13
	v_fmac_f32_e32 v81, v82, v12
	v_fma_f32 v10, -v10, v81, v13
	v_div_fmas_f32 v10, v10, v12, v81
	v_div_fixup_f32 v82, v10, v11, v248
	v_pk_mul_f32 v[10:11], v[44:45], v[82:83] op_sel_hi:[1,0]
	v_pk_mul_f32 v[12:13], v[46:47], v[82:83] op_sel_hi:[1,0]
	v_pk_fma_f32 v[10:11], v[60:61], v[80:81], v[10:11] op_sel_hi:[1,0,1] neg_lo:[0,0,1] neg_hi:[0,0,1]
	v_pk_mul_f32 v[60:61], v[66:67], v[82:83] op_sel_hi:[1,0]
	v_pk_fma_f32 v[12:13], v[62:63], v[80:81], v[12:13] op_sel_hi:[1,0,1] neg_lo:[0,0,1] neg_hi:[0,0,1]
	v_pk_fma_f32 v[66:67], v[98:99], v[80:81], v[60:61] op_sel_hi:[1,0,1] neg_lo:[0,0,1] neg_hi:[0,0,1]
	global_load_dwordx4 v[60:63], v[208:209], off
	v_pk_mul_f32 v[64:65], v[64:65], v[82:83] op_sel_hi:[1,0]
	v_pk_mul_f32 v[70:71], v[70:71], v[82:83] op_sel_hi:[1,0]
	v_pk_fma_f32 v[64:65], v[96:97], v[80:81], v[64:65] op_sel_hi:[1,0,1] neg_lo:[0,0,1] neg_hi:[0,0,1]
	v_pk_mul_f32 v[68:69], v[68:69], v[82:83] op_sel_hi:[1,0]
	v_pk_mul_f32 v[88:89], v[64:65], v[64:65]
	v_pk_mul_f32 v[74:75], v[74:75], v[82:83] op_sel_hi:[1,0]
	v_pk_mul_f32 v[72:73], v[72:73], v[82:83] op_sel_hi:[1,0]
	v_pk_mul_f32 v[78:79], v[78:79], v[82:83] op_sel_hi:[1,0]
	v_pk_mul_f32 v[76:77], v[76:77], v[82:83] op_sel_hi:[1,0]
	v_pk_mul_f32 v[34:35], v[34:35], v[82:83] op_sel_hi:[1,0]
	v_pk_mul_f32 v[32:33], v[32:33], v[82:83] op_sel_hi:[1,0]
	v_pk_mul_f32 v[38:39], v[38:39], v[82:83] op_sel_hi:[1,0]
	v_pk_mul_f32 v[36:37], v[36:37], v[82:83] op_sel_hi:[1,0]
	v_pk_mul_f32 v[42:43], v[42:43], v[82:83] op_sel_hi:[1,0]
	v_pk_mul_f32 v[40:41], v[40:41], v[82:83] op_sel_hi:[1,0]
	v_pk_mul_f32 v[86:87], v[66:67], v[66:67]
	v_pk_fma_f32 v[70:71], v[102:103], v[80:81], v[70:71] op_sel_hi:[1,0,1] neg_lo:[0,0,1] neg_hi:[0,0,1]
	v_pk_fma_f32 v[68:69], v[100:101], v[80:81], v[68:69] op_sel_hi:[1,0,1] neg_lo:[0,0,1] neg_hi:[0,0,1]
	v_pk_fma_f32 v[74:75], v[106:107], v[80:81], v[74:75] op_sel_hi:[1,0,1] neg_lo:[0,0,1] neg_hi:[0,0,1]
	v_pk_fma_f32 v[72:73], v[104:105], v[80:81], v[72:73] op_sel_hi:[1,0,1] neg_lo:[0,0,1] neg_hi:[0,0,1]
	v_pk_fma_f32 v[78:79], v[110:111], v[80:81], v[78:79] op_sel_hi:[1,0,1] neg_lo:[0,0,1] neg_hi:[0,0,1]
	v_pk_fma_f32 v[76:77], v[108:109], v[80:81], v[76:77] op_sel_hi:[1,0,1] neg_lo:[0,0,1] neg_hi:[0,0,1]
	v_pk_fma_f32 v[50:51], v[50:51], v[80:81], v[34:35] op_sel_hi:[1,0,1] neg_lo:[0,0,1] neg_hi:[0,0,1]
	v_pk_fma_f32 v[48:49], v[48:49], v[80:81], v[32:33] op_sel_hi:[1,0,1] neg_lo:[0,0,1] neg_hi:[0,0,1]
	v_pk_fma_f32 v[38:39], v[54:55], v[80:81], v[38:39] op_sel_hi:[1,0,1] neg_lo:[0,0,1] neg_hi:[0,0,1]
	v_pk_fma_f32 v[36:37], v[52:53], v[80:81], v[36:37] op_sel_hi:[1,0,1] neg_lo:[0,0,1] neg_hi:[0,0,1]
	v_pk_fma_f32 v[42:43], v[58:59], v[80:81], v[42:43] op_sel_hi:[1,0,1] neg_lo:[0,0,1] neg_hi:[0,0,1]
	v_pk_fma_f32 v[40:41], v[56:57], v[80:81], v[40:41] op_sel_hi:[1,0,1] neg_lo:[0,0,1] neg_hi:[0,0,1]
	v_add_f32_e32 v80, v88, v89
	v_add_f32_e32 v80, v86, v80
	v_pk_mul_f32 v[92:93], v[68:69], v[68:69]
	v_add_f32_e32 v80, v87, v80
	v_add_f32_e32 v80, v92, v80
	v_pk_mul_f32 v[90:91], v[70:71], v[70:71]
	v_add_f32_e32 v80, v93, v80
	v_add_f32_e32 v80, v90, v80
	v_pk_mul_f32 v[96:97], v[72:73], v[72:73]
	v_add_f32_e32 v80, v91, v80
	v_add_f32_e32 v80, v96, v80
	v_pk_mul_f32 v[94:95], v[74:75], v[74:75]
	v_add_f32_e32 v80, v97, v80
	v_add_f32_e32 v80, v94, v80
	v_pk_mul_f32 v[100:101], v[76:77], v[76:77]
	v_add_f32_e32 v80, v95, v80
	v_add_f32_e32 v80, v100, v80
	v_pk_mul_f32 v[98:99], v[78:79], v[78:79]
	v_add_f32_e32 v80, v101, v80
	v_add_f32_e32 v80, v98, v80
	v_pk_mul_f32 v[32:33], v[48:49], v[48:49]
	v_add_f32_e32 v80, v99, v80
	v_add_f32_e32 v32, v32, v80
	v_pk_mul_f32 v[34:35], v[50:51], v[50:51]
	v_add_f32_e32 v32, v33, v32
	v_add_f32_e32 v32, v34, v32
	v_pk_mul_f32 v[52:53], v[36:37], v[36:37]
	v_add_f32_e32 v32, v35, v32
	v_add_f32_e32 v32, v52, v32
	v_pk_mul_f32 v[54:55], v[38:39], v[38:39]
	v_add_f32_e32 v32, v53, v32
	v_add_f32_e32 v32, v54, v32
	v_pk_mul_f32 v[56:57], v[40:41], v[40:41]
	v_add_f32_e32 v32, v55, v32
	v_add_f32_e32 v32, v56, v32
	v_pk_mul_f32 v[58:59], v[42:43], v[42:43]
	v_add_f32_e32 v32, v57, v32
	v_add_f32_e32 v32, v58, v32
	v_pk_mul_f32 v[84:85], v[10:11], v[10:11]
	v_add_f32_e32 v32, v59, v32
	v_add_f32_e32 v32, v84, v32
	v_pk_mul_f32 v[46:47], v[12:13], v[12:13]
	v_add_f32_e32 v32, v85, v32
	v_add_f32_e32 v32, v46, v32
	v_add_f32_e32 v32, v47, v32
	ds_bpermute_b32 v33, v242, v32
	v_lshl_add_u32 v44, s37, 14, v215
	v_ashrrev_i32_e32 v45, 31, v44
	v_lshlrev_b64 v[44:45], 11, v[44:45]
	v_lshl_add_u64 v[44:45], s[44:45], 0, v[44:45]
	s_waitcnt lgkmcnt(0)
; DI unsigned pack2(float a, float b) { f2_t v = {a, b}; return __builtin_bit_cast(unsigned, __builtin_convertvector(v, bf2_t)); }
; DI void phase_diff(KP p, int layer, u16* sm) {
;     ...
;     const float inv = rsqrtf(ss * (1.f / 64.f) + 1e-6f) * (1.f - lam_init);
;     u16* op = p.o + (size_t)(b * S + tq) * 1024 + head * 64;
; #pragma unroll
;     for (int mb = 0; mb < 2; ++mb)
; #pragma unroll
;       for (int g = 0; g < 4; ++g) {
;         const int d = mb * 32 + 8 * g + 4 * hh;
;         const float4 g4 = *(const float4*)(sg + d);
;         *(uint2*)(op + d) = make_uint2(pack2(O[0][mb][4 * g] * inv * g4.x, O[0][mb][4 * g + 1] * inv * g4.y),
;                                        pack2(O[0][mb][4 * g + 2] * inv * g4.z, O[0][mb][4 * g + 3] * inv * g4.w));
;       }
	v_add_f32_e32 v32, v32, v33
	v_fmamk_f32 v32, v32, 0x3c800000, v225
	v_cmp_gt_f32_e32 vcc, s33, v32
	v_mul_f32_e32 v33, 0x4b800000, v32
	v_lshl_add_u64 v[44:45], v[44:45], 0, s[30:31]
	v_cndmask_b32_e32 v32, v32, v33, vcc
	v_rsq_f32_e32 v32, v32
	v_mov_b32_e32 v215, v1
	v_lshl_add_u64 v[44:45], v[44:45], 0, v[214:215]
	v_mul_f32_e32 v33, 0x45800000, v32
	v_cndmask_b32_e32 v32, v32, v33, vcc
	v_mul_f32_e32 v46, v236, v32
	v_pk_mul_f32 v[32:33], v[64:65], v[46:47] op_sel_hi:[1,0]
	v_pk_mul_f32 v[34:35], v[66:67], v[46:47] op_sel_hi:[1,0]
	global_load_dwordx4 v[112:115], v[208:209], off offset:32
	global_load_dwordx4 v[116:119], v[208:209], off offset:64
	global_load_dwordx4 v[120:123], v[208:209], off offset:96
	global_load_dwordx4 v[124:127], v[208:209], off offset:128
	global_load_dwordx4 v[128:131], v[208:209], off offset:160
	global_load_dwordx4 v[132:135], v[208:209], off offset:192
	global_load_dwordx4 v[136:139], v[208:209], off offset:224
	s_waitcnt vmcnt(0)
	v_pk_mul_f32 v[32:33], v[60:61], v[32:33]
	v_pk_mul_f32 v[34:35], v[62:63], v[34:35]
	v_cvt_pk_bf16_f32 v32, v32, v33
	v_cvt_pk_bf16_f32 v33, v34, v35
	global_store_dwordx2 v[44:45], v[32:33], off
	v_pk_mul_f32 v[52:53], v[68:69], v[46:47] op_sel_hi:[1,0]
	v_pk_mul_f32 v[48:49], v[48:49], v[46:47] op_sel_hi:[1,0]
	v_pk_mul_f32 v[36:37], v[36:37], v[46:47] op_sel_hi:[1,0]
	v_pk_mul_f32 v[10:11], v[10:11], v[46:47] op_sel_hi:[1,0]
	v_pk_mul_f32 v[12:13], v[12:13], v[46:47] op_sel_hi:[1,0]
	v_pk_mul_f32 v[32:33], v[112:113], v[52:53]
	v_pk_mul_f32 v[52:53], v[70:71], v[46:47] op_sel_hi:[1,0]
	v_cvt_pk_bf16_f32 v32, v32, v33
	v_pk_mul_f32 v[34:35], v[114:115], v[52:53]
	v_pk_mul_f32 v[52:53], v[72:73], v[46:47] op_sel_hi:[1,0]
	v_cvt_pk_bf16_f32 v33, v34, v35
	global_store_dwordx2 v[44:45], v[32:33], off offset:16
	v_pk_mul_f32 v[32:33], v[116:117], v[52:53]
	v_pk_mul_f32 v[52:53], v[74:75], v[46:47] op_sel_hi:[1,0]
	v_cvt_pk_bf16_f32 v32, v32, v33
	v_pk_mul_f32 v[34:35], v[118:119], v[52:53]
	v_pk_mul_f32 v[52:53], v[76:77], v[46:47] op_sel_hi:[1,0]
	v_cvt_pk_bf16_f32 v33, v34, v35
	global_store_dwordx2 v[44:45], v[32:33], off offset:32
	v_pk_mul_f32 v[32:33], v[120:121], v[52:53]
	v_pk_mul_f32 v[52:53], v[78:79], v[46:47] op_sel_hi:[1,0]
	v_cvt_pk_bf16_f32 v32, v32, v33
	v_pk_mul_f32 v[34:35], v[122:123], v[52:53]
	s_nop 0
	v_cvt_pk_bf16_f32 v33, v34, v35
	global_store_dwordx2 v[44:45], v[32:33], off offset:48
	v_pk_mul_f32 v[32:33], v[124:125], v[48:49]
	v_pk_mul_f32 v[48:49], v[50:51], v[46:47] op_sel_hi:[1,0]
	v_cvt_pk_bf16_f32 v32, v32, v33
	v_pk_mul_f32 v[34:35], v[126:127], v[48:49]
	s_nop 0
	v_cvt_pk_bf16_f32 v33, v34, v35
	global_store_dwordx2 v[44:45], v[32:33], off offset:64
	v_pk_mul_f32 v[32:33], v[128:129], v[36:37]
	v_pk_mul_f32 v[36:37], v[38:39], v[46:47] op_sel_hi:[1,0]
	v_cvt_pk_bf16_f32 v32, v32, v33
	v_pk_mul_f32 v[34:35], v[130:131], v[36:37]
	v_pk_mul_f32 v[36:37], v[40:41], v[46:47] op_sel_hi:[1,0]
	v_cvt_pk_bf16_f32 v33, v34, v35
	global_store_dwordx2 v[44:45], v[32:33], off offset:80
	v_pk_mul_f32 v[32:33], v[132:133], v[36:37]
	v_pk_mul_f32 v[36:37], v[42:43], v[46:47] op_sel_hi:[1,0]
	v_cvt_pk_bf16_f32 v32, v32, v33
	v_pk_mul_f32 v[34:35], v[134:135], v[36:37]
	s_nop 0
	v_cvt_pk_bf16_f32 v33, v34, v35
	global_store_dwordx2 v[44:45], v[32:33], off offset:96
	v_pk_mul_f32 v[10:11], v[136:137], v[10:11]
	v_pk_mul_f32 v[12:13], v[138:139], v[12:13]
	v_cvt_pk_bf16_f32 v10, v10, v11
	v_cvt_pk_bf16_f32 v11, v12, v13
	global_store_dwordx2 v[44:45], v[10:11], off offset:112
	s_cbranch_scc0 .LBB0_474
